# static s_setprio 1 for waves 4-7 during the attention items and the retention-output phase (one wave per SIMD leads, MFMA and softmax VALU of the two waves overlap)
# speedup vs baseline: 1.0108x; 1.0000x over previous
.LBB0_27:
	v_readlane_b32 s2, v255, 21
	s_cmp_lt_i32 s2, 5
	s_mov_b64 s[2:3], -1
	s_cbranch_scc0 .LBB0_49
	v_readfirstlane_b32 s98, v140
	s_nop 3
	s_bitcmp1_b32 s98, 8
	s_cbranch_scc0 .Lmy_rp
	s_setprio 1
.Lmy_rp:
	v_readlane_b32 s2, v255, 12
	v_readlane_b32 s3, v255, 13
	s_and_b64 s[2:3], s[2:3], exec
	s_movk_i32 s2, 0x410
	s_cselect_b32 s15, s2, 0x400
	v_and_b32_e32 v50, 3, v140
	s_cmp_lt_i32 s57, s15
	v_readfirstlane_b32 s16, v140
	v_ashrrev_i32_e32 v166, 2, v140
	s_cselect_b64 s[2:3], -1, 0
	s_cmp_ge_i32 s57, s15
	v_lshlrev_b32_e32 v165, 4, v50
	s_cbranch_scc1 .LBB0_30
	v_readlane_b32 s10, v253, 2
	s_waitcnt vmcnt(0)
	v_mov_b64_e32 v[2:3], s[72:73]
	v_add_u32_e32 v0, s10, v166
	v_mad_i64_i32 v[2:3], s[10:11], v0, s64, v[2:3]
	v_readlane_b32 s10, v254, 42
	v_readlane_b32 s11, v254, 43
	s_mov_b32 s11, s17
	v_lshlrev_b32_e32 v0, 1, v165
	v_lshl_add_u64 v[2:3], v[2:3], 0, s[10:11]
	v_lshl_add_u64 v[2:3], v[2:3], 0, v[0:1]
	global_load_dwordx4 v[18:21], v[2:3], off offset:528
	global_load_dwordx4 v[22:25], v[2:3], off offset:512
	global_load_dwordx4 v[26:29], v[2:3], off offset:1040
	global_load_dwordx4 v[30:33], v[2:3], off offset:1024
	s_mov_b32 s20, s10
	v_writelane_b32 v254, s20, 42
	s_nop 1
	v_writelane_b32 v254, s21, 43

.LBB0_48:
	s_setprio 0
	s_mov_b64 s[2:3], 0

.LBB0_95:
	s_and_b64 vcc, exec, s[2:3]
	s_cbranch_vccz .LBB0_265
	v_writelane_b32 v255, s56, 30
	v_and_b32_e32 v0, 3, v140
	v_readlane_b32 s2, v255, 12
	v_readlane_b32 s3, v255, 13
	s_and_b64 s[2:3], s[2:3], exec
	s_movk_i32 s2, 0x410
	s_cselect_b32 s15, s2, 0x400
	s_cmp_lt_i32 s57, s15
	v_writelane_b32 v255, s57, 34
	s_cselect_b64 s[2:3], -1, 0
	v_writelane_b32 v255, s2, 48
	v_bfe_u32 v147, v140, 4, 2
	v_ashrrev_i32_e32 v139, 2, v140
	v_writelane_b32 v255, s3, 49
	v_lshlrev_b32_e32 v142, 4, v0
	v_readlane_b32 s2, v255, 14
	v_readlane_b32 s3, v255, 15
	s_lshl_b32 s2, s2, 3
	s_ashr_i32 s3, s2, 31
	v_lshlrev_b32_e32 v141, 5, v0
	v_lshlrev_b32_e32 v0, 3, v140
	v_writelane_b32 v255, s2, 36
	v_bfe_u32 v156, v140, 2, 2
	s_waitcnt vmcnt(0)
	v_mul_lo_u32 v2, v139, s65
	v_lshlrev_b32_e32 v144, 2, v147
	v_and_b32_e32 v155, 24, v0
	v_writelane_b32 v255, s3, 37
	v_and_b32_e32 v145, 15, v140
	v_lshlrev_b32_e32 v146, 3, v147
	v_or_b32_e32 v154, v144, v156
	v_add_u32_e32 v143, 0, v2
	v_lshl_add_u32 v158, v147, 4, 0
	v_add_u32_e32 v157, 0, v155
	s_mov_b32 s63, 0
	v_lshlrev_b32_e32 v148, 1, v144
	v_and_b32_e32 v231, 3, v145
	v_lshlrev_b32_e32 v232, 3, v231
	v_mov_b32_e32 v233, 0
	v_bfe_u32 v230, v145, 2, 2
	v_lshl_or_b32 v230, v230, 2, v147
	v_lshl_add_u32 v231, v231, 4, v230
	v_lshlrev_b32_e32 v231, 2, v231
	v_sub_u32_e32 v230, v230, v145
	v_readfirstlane_b32 s98, v140
	s_nop 3
	s_bitcmp1_b32 s98, 8
	s_cbranch_scc0 .Lmy_ap
	s_setprio 1
.Lmy_ap:
	s_branch .LBB0_98
.LBB0_97:
	s_add_i32 s2, s63, 1
	v_readlane_b32 s3, v253, 39
	s_cmp_eq_u32 s63, s3
	s_mov_b32 s63, s2
	s_cbranch_scc1 .LBB0_253

.LBB0_253:
	s_setprio 0
	v_readlane_b32 s2, v255, 12
	v_readlane_b32 s3, v255, 13
	s_and_b64 s[2:3], s[2:3], exec
	v_readlane_b32 s20, v254, 30
	s_mul_hi_u32 s3, s15, s20
	v_readlane_b32 s16, v254, 29
	s_movk_i32 s2, 0x104
	s_mul_i32 s3, s3, s16
	s_cselect_b32 s2, s2, 0x100
	s_sub_i32 s3, s15, s3
	s_sub_i32 s10, s3, s16
	s_cmp_ge_u32 s3, s16
	s_cselect_b32 s3, s10, s3
	s_sub_i32 s10, s3, s16
	s_cmp_ge_u32 s3, s16
	s_cselect_b32 s3, s10, s3
	s_sub_i32 s3, s96, s3
	s_ashr_i32 s10, s3, 31
	s_abs_i32 s3, s3
	s_mul_hi_u32 s11, s3, s20
	s_mul_i32 s11, s11, s16
	s_sub_i32 s3, s3, s11
	s_sub_i32 s11, s3, s16
	s_cmp_ge_u32 s3, s16
	s_cselect_b32 s3, s11, s3
	s_sub_i32 s11, s3, s16
	s_cmp_ge_u32 s3, s16
	s_cselect_b32 s3, s11, s3
	s_xor_b32 s3, s3, s10
	s_sub_i32 s3, s3, s10
	v_readlane_b32 s57, v255, 34
	s_add_i32 s10, s3, s57
	s_ashr_i32 s15, s10, 31
	s_abs_i32 s10, s10
	s_mul_hi_u32 s11, s10, s20
	s_mul_i32 s11, s11, s16
	s_sub_i32 s10, s10, s11
	s_sub_i32 s11, s10, s16
	s_cmp_ge_u32 s10, s16
	s_cselect_b32 s10, s11, s10
	s_sub_i32 s11, s10, s16
	s_cmp_ge_u32 s10, s16
	s_cselect_b32 s10, s11, s10
	v_readlane_b32 s22, v255, 16
	s_xor_b32 s16, s10, s15
	v_lshlrev_b32_e32 v0, 1, v146
	v_readlane_b32 s23, v255, 17
	s_sub_i32 s40, s16, s15
	v_readlane_b32 s10, v255, 14
	v_lshl_add_u64 v[2:3], s[22:23], 0, v[0:1]
	s_mov_b64 s[22:23], 0x1700000
	s_cmp_lt_i32 s40, s2
	s_mov_b32 s20, s10
	v_lshl_add_u64 v[74:75], v[2:3], 0, s[22:23]
	v_ashrrev_i32_e32 v0, 7, v140
	s_movk_i32 s22, 0x4800
	s_cselect_b64 s[42:43], -1, 0
	v_readlane_b32 s11, v255, 15
	s_lshl_b32 s10, s10, 8
	s_lshl_b32 s20, s20, 9
	v_and_b32_e32 v2, 0x7f, v140
	v_lshlrev_b32_e32 v76, 6, v0
	v_mul_lo_u32 v0, v0, s22
	s_ashr_i32 s11, s10, 31
	s_ashr_i32 s21, s20, 31
	v_add_u32_e32 v0, 0, v0
	v_mul_u32_u24_e32 v3, 0x90, v2
	v_or_b32_e32 v4, v146, v156
	v_lshl_or_b32 v2, s16, 7, v2
	s_lshl_b32 s15, s15, 7
	s_ashr_i32 s41, s40, 31
	v_readlane_b32 s74, v254, 59
	v_readlane_b32 s82, v254, 61
	v_ashrrev_i32_e32 v77, 31, v76
	v_mad_u32_u24 v84, v4, s65, v157
	v_subrev_u32_e32 v85, s15, v2
	s_lshl_b64 s[44:45], s[40:41], 7
	s_mov_b32 s15, 0
	s_lshl_b64 s[46:47], s[10:11], 2
	s_lshl_b64 s[48:49], s[20:21], 2
	v_add_u32_e32 v86, v0, v3
	v_readlane_b32 s75, v254, 60
	v_readlane_b32 s83, v254, 62
	v_readlane_b32 s56, v255, 30
	s_branch .LBB0_255
